# cache policy: MLA attention-output stores non-temporal (keep the K/V working set in L2)
# baseline (speedup 1.0000x reference)
.Lmla_fin_join:
	v_add_f32_e32 v34, 0, v82
	v_add_f32_e32 v34, v83, v34
	v_add_f32_e32 v34, v84, v34
	v_add_f32_e32 v34, v85, v34
	v_add_f32_e32 v34, v86, v34
	v_add_f32_e32 v34, v87, v34
	v_add_f32_e32 v34, v88, v34
	v_add_f32_e32 v34, v89, v34
	v_add_f32_e32 v34, v90, v34
	v_add_f32_e32 v34, v91, v34
	v_add_f32_e32 v34, v92, v34
	v_add_f32_e32 v34, v93, v34
	v_add_f32_e32 v34, v94, v34
	v_add_f32_e32 v34, v95, v34
	v_add_f32_e32 v34, v96, v34
	v_add_f32_e32 v34, v97, v34
	v_add_f32_e32 v34, v99, v34
	v_add_f32_e32 v34, v100, v34
	v_add_f32_e32 v34, v101, v34
	v_add_f32_e32 v34, v102, v34
	v_add_f32_e32 v34, v103, v34
	v_add_f32_e32 v34, v104, v34
	v_add_f32_e32 v34, v105, v34
	v_add_f32_e32 v34, v106, v34
	v_add_f32_e32 v34, v74, v34
	v_add_f32_e32 v34, v75, v34
	v_add_f32_e32 v34, v76, v34
	v_add_f32_e32 v34, v77, v34
	v_add_f32_e32 v34, v78, v34
	v_add_f32_e32 v34, v79, v34
	v_add_f32_e32 v34, v80, v34
	v_add_f32_e32 v34, v81, v34
	v_add_f32_e32 v34, v107, v34
	v_add_f32_e32 v34, v108, v34
	v_add_f32_e32 v34, v110, v34
	v_add_f32_e32 v34, v111, v34
	v_add_f32_e32 v34, v113, v34
	v_add_f32_e32 v34, v114, v34
	v_add_f32_e32 v34, v70, v34
	v_add_f32_e32 v34, v71, v34
	v_add_f32_e32 v34, v72, v34
	v_add_f32_e32 v34, v73, v34
	v_add_f32_e32 v34, v115, v34
	v_add_f32_e32 v34, v66, v34
	v_add_f32_e32 v34, v62, v34
	v_add_f32_e32 v34, v63, v34
	v_add_f32_e32 v34, v64, v34
	v_add_f32_e32 v34, v65, v34
	v_add_f32_e32 v34, v67, v34
	v_add_f32_e32 v34, v68, v34
	v_add_f32_e32 v34, v69, v34
	v_add_f32_e32 v34, v58, v34
	v_add_f32_e32 v34, v59, v34
	v_add_f32_e32 v34, v60, v34
	v_add_f32_e32 v34, v61, v34
	v_add_f32_e32 v34, v54, v34
	v_add_f32_e32 v34, v55, v34
	v_add_f32_e32 v34, v56, v34
	v_add_f32_e32 v34, v57, v34
	v_add_f32_e32 v34, v50, v34
	v_add_f32_e32 v34, v46, v34
	v_add_f32_e32 v34, v47, v34
	v_add_f32_e32 v34, v48, v34
	v_add_f32_e32 v34, v49, v34
	v_add_f32_e32 v1, v34, v1
	s_setprio 0
	ds_bpermute_b32 v36, v190, v1
	v_lshl_add_u64 v[34:35], s[10:11], 0, v[158:159]
	v_lshl_add_u64 v[34:35], v[34:35], 0, v[134:135]
	s_add_i32 s48, s48, s33
	s_cmpk_gt_i32 s48, 0x3ff
	s_waitcnt lgkmcnt(0)
	v_add_f32_e32 v1, v1, v36
	v_div_scale_f32 v36, s[10:11], v1, v1, 1.0
	v_rcp_f32_e32 v37, v36
	v_div_scale_f32 v38, vcc, 1.0, v1, 1.0
	v_fma_f32 v39, -v36, v37, 1.0
	v_fmac_f32_e32 v37, v39, v37
	v_mul_f32_e32 v39, v38, v37
	v_fma_f32 v40, -v36, v39, v38
	v_fmac_f32_e32 v39, v40, v37
	v_fma_f32 v36, -v36, v39, v38
	v_div_fmas_f32 v36, v36, v37, v39
	v_div_fixup_f32 v36, v36, v1, 1.0
	v_pk_mul_f32 v[18:19], v[18:19], v[36:37] op_sel_hi:[1,0]
	v_pk_mul_f32 v[20:21], v[20:21], v[36:37] op_sel_hi:[1,0]
	v_pk_mul_f32 v[2:3], v[2:3], v[36:37] op_sel_hi:[1,0]
	v_pk_mul_f32 v[4:5], v[4:5], v[36:37] op_sel_hi:[1,0]
	v_cvt_pk_bf16_f32 v18, v18, v19
	v_cvt_pk_bf16_f32 v19, v20, v21
	v_cvt_pk_bf16_f32 v2, v2, v3
	v_cvt_pk_bf16_f32 v3, v4, v5
	global_store_dwordx2 v[34:35], v[18:19], off nt
	v_pk_mul_f32 v[18:19], v[22:23], v[36:37] op_sel_hi:[1,0]
	v_pk_mul_f32 v[20:21], v[24:25], v[36:37] op_sel_hi:[1,0]
	global_store_dwordx2 v[34:35], v[2:3], off offset:64 nt
	v_pk_mul_f32 v[2:3], v[6:7], v[36:37] op_sel_hi:[1,0]
	v_pk_mul_f32 v[4:5], v[8:9], v[36:37] op_sel_hi:[1,0]
	v_cvt_pk_bf16_f32 v18, v18, v19
	v_cvt_pk_bf16_f32 v19, v20, v21
	v_cvt_pk_bf16_f32 v2, v2, v3
	v_cvt_pk_bf16_f32 v3, v4, v5
	global_store_dwordx2 v[34:35], v[18:19], off offset:16 nt
	v_pk_mul_f32 v[18:19], v[26:27], v[36:37] op_sel_hi:[1,0]
	v_pk_mul_f32 v[20:21], v[28:29], v[36:37] op_sel_hi:[1,0]
	global_store_dwordx2 v[34:35], v[2:3], off offset:80 nt
	v_pk_mul_f32 v[2:3], v[10:11], v[36:37] op_sel_hi:[1,0]
	v_pk_mul_f32 v[4:5], v[12:13], v[36:37] op_sel_hi:[1,0]
	v_cvt_pk_bf16_f32 v18, v18, v19
	v_cvt_pk_bf16_f32 v19, v20, v21
	v_cvt_pk_bf16_f32 v2, v2, v3
	v_cvt_pk_bf16_f32 v3, v4, v5
	global_store_dwordx2 v[34:35], v[18:19], off offset:32 nt
	v_pk_mul_f32 v[18:19], v[30:31], v[36:37] op_sel_hi:[1,0]
	v_pk_mul_f32 v[20:21], v[32:33], v[36:37] op_sel_hi:[1,0]
	global_store_dwordx2 v[34:35], v[2:3], off offset:96 nt
	v_pk_mul_f32 v[2:3], v[14:15], v[36:37] op_sel_hi:[1,0]
	v_pk_mul_f32 v[4:5], v[16:17], v[36:37] op_sel_hi:[1,0]
	v_cvt_pk_bf16_f32 v18, v18, v19
	v_cvt_pk_bf16_f32 v19, v20, v21
	v_cvt_pk_bf16_f32 v2, v2, v3
	v_cvt_pk_bf16_f32 v3, v4, v5
	global_store_dwordx2 v[34:35], v[18:19], off offset:48 nt
	global_store_dwordx2 v[34:35], v[2:3], off offset:112 nt
	s_cbranch_scc1 .LBB0_828
